# v41 plus NA scores: exec save/restore around each masked bias add replaced by in-place add + v_cndmask select (dst pre-initialised to -inf)
# baseline (speedup 1.0000x reference)
; #define LAS __attribute__((address_space(3)))
; #define MFMA32(a, b, c) __builtin_amdgcn_mfma_f32_16x16x32_bf16((a), (b), (c), 0, 0, 0)
; DI void na_phase(LAS unsigned char* lds, const Args& A, const bf16* proj, bf16* nao, int T, int nB, unsigned* counter, int tid_in) {
;     ...
;             for (int rr = 0; rr < 4; ++rr) { const int kr = rs + 4 * kh + rr, sl = kr & 7;
; #pragma unroll
;                 for (int ct = 0; ct < 2; ++ct) { const int cm = cs0 + 16 * ct + l15; f32x4 acc = (f32x4){0.f, 0.f, 0.f, 0.f};
; #pragma unroll
;                     for (int ks = 0; ks < 2; ++ks) { const bf16x8 kf = *(const LAS bf16x8*)(lds + NA_K + sl * 8192 + cm * 128 + (((4 * ks + g) ^ ((cm >> 1) & 7)) * 16)); acc = MFMA32(kf, qf[ks], acc); }
; #pragma unroll
;                     for (int e = 0; e < 4; ++e) { const int cc = cs0 + 16 * ct + 4 * g + e; const bool valid = (cc >= csq) && (cc < csq + 16);
;                         const int bi = (kr - r + 7) * 31 + min(max(cc - cq + 15, 0), 30);
;                         const float sv = valid ? acc[e] + BI[bi] : -INFINITY; acc[e] = sv; mx = fmaxf(mx, sv); }
;                     sT[rr][ct] = acc; } }
.LBB0_337:
	v_add_u32_e32 v31, s38, v71
	v_lshlrev_b32_e32 v24, 13, v31
	v_and_b32_e32 v28, 0xe000, v24
	v_add_u32_e32 v30, 0, v28
	v_add_u32_e32 v29, v30, v91
	v_add_u32_e32 v24, v29, v92
	ds_read_b128 v[24:27], v24
	v_add_u32_e32 v29, v29, v93
	ds_read_b128 v[58:61], v29
	s_add_i32 s0, s19, s38
	v_add_u32_e32 v29, s0, v57
	v_mul_lo_u32 v29, v29, s88
	v_add_u32_e32 v38, s87, v29
	v_add_u32_e32 v29, 0xfffff080, v38
	v_mov_b32_e32 v63, 0xff800000
	v_lshl_add_u32 v252, v94, 2, v29
	ds_read_b32 v252, v252 offset:868
	v_lshl_add_u32 v253, v95, 2, v29
	ds_read_b32 v253, v253 offset:868
	v_lshl_add_u32 v254, v96, 2, v29
	ds_read_b32 v254, v254 offset:868
	v_lshl_add_u32 v255, v97, 2, v29
	ds_read_b32 v255, v255 offset:868
	s_waitcnt lgkmcnt(5)
	v_mfma_f32_16x16x32_bf16 v[24:27], v[24:27], v[20:23], 0
	s_waitcnt lgkmcnt(4)
	v_mfma_f32_16x16x32_bf16 v[24:27], v[58:61], v[16:19], v[24:27]
	v_mov_b32_e32 v59, 0xff800000
	s_waitcnt lgkmcnt(0)
	s_nop 6
	v_add_f32_e32 v252, v24, v252
	v_cndmask_b32_e64 v63, v63, v252, s[14:15]
	v_add_f32_e32 v253, v25, v253
	v_cndmask_b32_e64 v59, v59, v253, s[16:17]
	v_mov_b32_e32 v56, 0xff800000
	v_mov_b32_e32 v62, 0xff800000
	v_add_f32_e32 v254, v26, v254
	v_cndmask_b32_e64 v62, v62, v254, s[48:49]
	v_add_f32_e32 v255, v27, v255
	v_cndmask_b32_e64 v56, v56, v255, s[50:51]
	v_add_u32_e32 v30, v30, v98
	v_add_u32_e32 v24, v30, v92
	ds_read_b128 v[24:27], v24
	v_add_u32_e32 v30, v30, v93
	ds_read_b128 v[64:67], v30
	v_mov_b32_e32 v39, 0xff800000
	v_lshl_add_u32 v252, v99, 2, v29
	ds_read_b32 v252, v252 offset:868
	v_lshl_add_u32 v253, v100, 2, v29
	ds_read_b32 v253, v253 offset:868
	v_lshl_add_u32 v254, v101, 2, v29
	ds_read_b32 v254, v254 offset:868
	v_lshl_add_u32 v255, v102, 2, v29
	ds_read_b32 v255, v255 offset:868
	s_waitcnt lgkmcnt(5)
	v_mfma_f32_16x16x32_bf16 v[24:27], v[24:27], v[20:23], 0
	s_waitcnt lgkmcnt(4)
	v_mfma_f32_16x16x32_bf16 v[24:27], v[64:67], v[16:19], v[24:27]
	v_mov_b32_e32 v65, 0xff800000
	s_waitcnt lgkmcnt(0)
	s_nop 6
	v_add_f32_e32 v252, v24, v252
	v_cndmask_b32_e64 v65, v65, v252, s[52:53]
	v_add_f32_e32 v253, v25, v253
	v_cndmask_b32_e64 v39, v39, v253, s[56:57]
	v_mov_b32_e32 v54, 0xff800000
	v_mov_b32_e32 v55, 0xff800000
	v_add_f32_e32 v254, v26, v254
	v_cndmask_b32_e64 v55, v55, v254, s[76:77]
	v_add_f32_e32 v255, v27, v255
	v_cndmask_b32_e64 v54, v54, v255, s[66:67]
	v_lshl_add_u32 v24, v31, 13, v212
	v_and_b32_e32 v29, 0xe000, v24
	v_add_u32_e32 v66, 0, v29
	v_add_u32_e32 v30, v66, v91
	v_add_u32_e32 v24, v30, v92
	ds_read_b128 v[24:27], v24
	v_add_u32_e32 v30, v30, v93
	ds_read_b128 v[104:107], v30
	v_add_u32_e32 v30, 0xfffff0fc, v38
	v_mov_b32_e32 v58, 0xff800000
	v_mov_b32_e32 v60, 0xff800000
	v_lshl_add_u32 v252, v94, 2, v30
	ds_read_b32 v252, v252 offset:868
	v_lshl_add_u32 v253, v95, 2, v30
	ds_read_b32 v253, v253 offset:868
	v_lshl_add_u32 v254, v96, 2, v30
	ds_read_b32 v254, v254 offset:868
	v_lshl_add_u32 v255, v97, 2, v30
	ds_read_b32 v255, v255 offset:868
	s_waitcnt lgkmcnt(5)
	v_mfma_f32_16x16x32_bf16 v[24:27], v[24:27], v[20:23], 0
	s_waitcnt lgkmcnt(4)
	v_mfma_f32_16x16x32_bf16 v[24:27], v[104:107], v[16:19], v[24:27]
	s_waitcnt lgkmcnt(0)
	s_nop 6
	v_add_f32_e32 v252, v24, v252
	v_cndmask_b32_e64 v60, v60, v252, s[14:15]
	v_add_f32_e32 v253, v25, v253
	v_cndmask_b32_e64 v58, v58, v253, s[16:17]
	v_mov_b32_e32 v61, 0xff800000
	v_mov_b32_e32 v64, 0xff800000
	v_add_f32_e32 v254, v26, v254
	v_cndmask_b32_e64 v64, v64, v254, s[48:49]
	v_add_f32_e32 v255, v27, v255
	v_cndmask_b32_e64 v61, v61, v255, s[50:51]
	v_add_u32_e32 v66, v66, v98
	v_add_u32_e32 v24, v66, v92
	ds_read_b128 v[24:27], v24
	v_add_u32_e32 v66, v66, v93
	ds_read_b128 v[104:107], v66
	v_mov_b32_e32 v66, 0xff800000
	v_mov_b32_e32 v67, 0xff800000
	v_lshl_add_u32 v252, v99, 2, v30
	ds_read_b32 v252, v252 offset:868
	v_lshl_add_u32 v253, v100, 2, v30
	ds_read_b32 v253, v253 offset:868
	v_lshl_add_u32 v254, v101, 2, v30
	ds_read_b32 v254, v254 offset:868
	v_lshl_add_u32 v255, v102, 2, v30
	ds_read_b32 v255, v255 offset:868
	s_waitcnt lgkmcnt(5)
	v_mfma_f32_16x16x32_bf16 v[24:27], v[24:27], v[20:23], 0
	s_waitcnt lgkmcnt(4)
	v_mfma_f32_16x16x32_bf16 v[24:27], v[104:107], v[16:19], v[24:27]
	s_waitcnt lgkmcnt(0)
	s_nop 6
	v_add_f32_e32 v252, v24, v252
	v_cndmask_b32_e64 v67, v67, v252, s[52:53]
	v_add_f32_e32 v253, v25, v253
	v_cndmask_b32_e64 v66, v66, v253, s[56:57]
	v_mov_b32_e32 v104, 0xff800000
	v_mov_b32_e32 v105, 0xff800000
	v_add_f32_e32 v254, v26, v254
	v_cndmask_b32_e64 v105, v105, v254, s[76:77]
	v_add_f32_e32 v255, v27, v255
	v_cndmask_b32_e64 v104, v104, v255, s[66:67]
	v_lshl_add_u32 v24, v31, 13, v213
	v_and_b32_e32 v30, 0xe000, v24
	v_add_u32_e32 v110, 0, v30
	v_add_u32_e32 v106, v110, v91
	v_add_u32_e32 v24, v106, v92
	ds_read_b128 v[24:27], v24
	v_add_u32_e32 v106, v106, v93
	ds_read_b128 v[106:109], v106
	v_add_u32_e32 v114, 0xfffff178, v38
	v_lshl_add_u32 v252, v94, 2, v114
	ds_read_b32 v252, v252 offset:868
	v_lshl_add_u32 v253, v95, 2, v114
	ds_read_b32 v253, v253 offset:868
	v_lshl_add_u32 v254, v96, 2, v114
	ds_read_b32 v254, v254 offset:868
	v_lshl_add_u32 v255, v97, 2, v114
	ds_read_b32 v255, v255 offset:868
	s_waitcnt lgkmcnt(5)
	v_mfma_f32_16x16x32_bf16 v[24:27], v[24:27], v[20:23], 0
	s_waitcnt lgkmcnt(4)
	v_mfma_f32_16x16x32_bf16 v[24:27], v[106:109], v[16:19], v[24:27]
	v_mov_b32_e32 v106, 0xff800000
	v_mov_b32_e32 v107, 0xff800000
	s_waitcnt lgkmcnt(0)
; #define LAS __attribute__((address_space(3)))
; #define MFMA32(a, b, c) __builtin_amdgcn_mfma_f32_16x16x32_bf16((a), (b), (c), 0, 0, 0)
; DI void na_phase(LAS unsigned char* lds, const Args& A, const bf16* proj, bf16* nao, int T, int nB, unsigned* counter, int tid_in) {
;     ...
;             for (int rr = 0; rr < 4; ++rr) { const int kr = rs + 4 * kh + rr, sl = kr & 7;
; #pragma unroll
;                 for (int ct = 0; ct < 2; ++ct) { const int cm = cs0 + 16 * ct + l15; f32x4 acc = (f32x4){0.f, 0.f, 0.f, 0.f};
; #pragma unroll
;                     for (int ks = 0; ks < 2; ++ks) { const bf16x8 kf = *(const LAS bf16x8*)(lds + NA_K + sl * 8192 + cm * 128 + (((4 * ks + g) ^ ((cm >> 1) & 7)) * 16)); acc = MFMA32(kf, qf[ks], acc); }
; #pragma unroll
;                     for (int e = 0; e < 4; ++e) { const int cc = cs0 + 16 * ct + 4 * g + e; const bool valid = (cc >= csq) && (cc < csq + 16);
;                         const int bi = (kr - r + 7) * 31 + min(max(cc - cq + 15, 0), 30);
;                         const float sv = valid ? acc[e] + BI[bi] : -INFINITY; acc[e] = sv; mx = fmaxf(mx, sv); }
;                     sT[rr][ct] = acc; } }
;             mx = fmaxf(mx, __shfl_xor(mx, 16)); mx = fmaxf(mx, __shfl_xor(mx, 32));
;             float lsum = 0.f;
; #pragma unroll
;             for (int rr = 0; rr < 4; ++rr)
; #pragma unroll
;                 for (int ct = 0; ct < 2; ++ct)
; #pragma unroll
;                     for (int e = 0; e < 4; ++e) { const float p = __expf(sT[rr][ct][e] - mx); sT[rr][ct][e] = p; lsum += p; }
	s_nop 6
	v_add_f32_e32 v252, v24, v252
	v_cndmask_b32_e64 v107, v107, v252, s[14:15]
	v_add_f32_e32 v253, v25, v253
	v_cndmask_b32_e64 v106, v106, v253, s[16:17]
	v_mov_b32_e32 v108, 0xff800000
	v_mov_b32_e32 v109, 0xff800000
	v_add_f32_e32 v254, v26, v254
	v_cndmask_b32_e64 v109, v109, v254, s[48:49]
	v_add_f32_e32 v255, v27, v255
	v_cndmask_b32_e64 v108, v108, v255, s[50:51]
	v_add_u32_e32 v110, v110, v98
	v_add_u32_e32 v24, v110, v92
	ds_read_b128 v[24:27], v24
	v_add_u32_e32 v110, v110, v93
	ds_read_b128 v[110:113], v110
	v_lshl_add_u32 v252, v99, 2, v114
	ds_read_b32 v252, v252 offset:868
	v_lshl_add_u32 v253, v100, 2, v114
	ds_read_b32 v253, v253 offset:868
	v_lshl_add_u32 v254, v101, 2, v114
	ds_read_b32 v254, v254 offset:868
	v_lshl_add_u32 v255, v102, 2, v114
	ds_read_b32 v255, v255 offset:868
	s_waitcnt lgkmcnt(5)
	v_mfma_f32_16x16x32_bf16 v[24:27], v[24:27], v[20:23], 0
	s_waitcnt lgkmcnt(4)
	v_mfma_f32_16x16x32_bf16 v[24:27], v[110:113], v[16:19], v[24:27]
	v_mov_b32_e32 v110, 0xff800000
	v_mov_b32_e32 v111, 0xff800000
	s_waitcnt lgkmcnt(0)
	s_nop 6
	v_add_f32_e32 v252, v24, v252
	v_cndmask_b32_e64 v111, v111, v252, s[52:53]
	v_add_f32_e32 v253, v25, v253
	v_cndmask_b32_e64 v110, v110, v253, s[56:57]
	v_mov_b32_e32 v112, 0xff800000
	v_mov_b32_e32 v113, 0xff800000
	v_add_f32_e32 v254, v26, v254
	v_cndmask_b32_e64 v113, v113, v254, s[76:77]
	v_add_f32_e32 v255, v27, v255
	v_cndmask_b32_e64 v112, v112, v255, s[66:67]
	v_lshl_add_u32 v24, v31, 13, v214
	v_and_b32_e32 v31, 0xe000, v24
	v_add_u32_e32 v116, 0, v31
	v_add_u32_e32 v114, v116, v91
	v_add_u32_e32 v24, v114, v92
	ds_read_b128 v[24:27], v24
	v_add_u32_e32 v114, v114, v93
	ds_read_b128 v[118:121], v114
	v_add_u32_e32 v38, 0xfffff1f4, v38
	v_mov_b32_e32 v114, 0xff800000
	v_mov_b32_e32 v115, 0xff800000
	v_lshl_add_u32 v252, v94, 2, v38
	ds_read_b32 v252, v252 offset:868
	v_lshl_add_u32 v253, v95, 2, v38
	ds_read_b32 v253, v253 offset:868
	s_waitcnt lgkmcnt(3)
	v_mfma_f32_16x16x32_bf16 v[24:27], v[24:27], v[20:23], 0
	s_waitcnt lgkmcnt(2)
	v_mfma_f32_16x16x32_bf16 v[24:27], v[118:121], v[16:19], v[24:27]
	s_waitcnt lgkmcnt(0)
	s_nop 6
	v_add_f32_e32 v252, v24, v252
	v_cndmask_b32_e64 v115, v115, v252, s[14:15]
	v_add_f32_e32 v253, v25, v253
	v_cndmask_b32_e64 v114, v114, v253, s[16:17]
	s_nop 1
	v_mov_b32_e32 v24, 0xff800000
	v_mov_b32_e32 v25, 0xff800000
	v_lshl_add_u32 v252, v96, 2, v38
	ds_read_b32 v252, v252 offset:868
	v_lshl_add_u32 v253, v97, 2, v38
	ds_read_b32 v253, v253 offset:868
	s_waitcnt lgkmcnt(0)
	s_nop 2
	v_add_f32_e32 v252, v26, v252
	v_cndmask_b32_e64 v25, v25, v252, s[48:49]
	v_add_f32_e32 v253, v27, v253
	v_cndmask_b32_e64 v24, v24, v253, s[50:51]
	v_add_u32_e32 v26, v116, v98
	v_add_u32_e32 v27, v26, v92
	ds_read_b128 v[116:119], v27
	v_add_u32_e32 v26, v26, v93
	s_waitcnt lgkmcnt(0)
	v_mfma_f32_16x16x32_bf16 v[20:23], v[116:119], v[20:23], 0
	ds_read_b128 v[116:119], v26
	s_waitcnt lgkmcnt(0)
	v_mfma_f32_16x16x32_bf16 v[16:19], v[116:119], v[16:19], v[20:23]
	s_nop 4
	v_mov_b32_e32 v20, 0xff800000
	v_mov_b32_e32 v21, 0xff800000
	v_lshl_add_u32 v252, v99, 2, v38
	ds_read_b32 v252, v252 offset:868
	v_lshl_add_u32 v253, v100, 2, v38
	ds_read_b32 v253, v253 offset:868
	v_lshl_add_u32 v254, v101, 2, v38
	ds_read_b32 v254, v254 offset:868
	v_lshl_add_u32 v255, v102, 2, v38
	ds_read_b32 v255, v255 offset:868
	s_waitcnt lgkmcnt(0)
	v_add_f32_e32 v252, v16, v252
	v_cndmask_b32_e64 v21, v21, v252, s[52:53]
	v_add_f32_e32 v253, v17, v253
	v_cndmask_b32_e64 v20, v20, v253, s[56:57]
	v_mov_b32_e32 v16, 0xff800000
	v_mov_b32_e32 v17, 0xff800000
	v_add_f32_e32 v254, v18, v254
	v_cndmask_b32_e64 v17, v17, v254, s[76:77]
	v_add_f32_e32 v255, v19, v255
	v_cndmask_b32_e64 v16, v16, v255, s[66:67]
	v_max3_f32 v18, v63, s89, v59
	v_max3_f32 v18, v18, v62, v56
	v_max3_f32 v18, v18, v65, v39
	v_max3_f32 v18, v18, v55, v54
	v_max3_f32 v18, v18, v60, v58
	v_max3_f32 v18, v18, v64, v61
	v_max3_f32 v18, v18, v67, v66
	v_max3_f32 v18, v18, v105, v104
	v_max3_f32 v18, v18, v107, v106
	v_max3_f32 v18, v18, v109, v108
	v_max3_f32 v18, v18, v111, v110
	v_max3_f32 v18, v18, v113, v112
	v_max3_f32 v18, v18, v115, v114
	v_max3_f32 v18, v18, v25, v24
	v_max3_f32 v18, v18, v21, v20
	v_max3_f32 v18, v18, v17, v16
	v_mov_b32_e32 v19, v18
	s_nop 1
	v_permlane16_swap_b32_e32 v19, v18
	v_max_f32_e32 v18, v18, v19
	v_mov_b32_e32 v19, v18
	s_nop 1
	v_permlane32_swap_b32_e32 v19, v18
	v_max_f32_e32 v38, v18, v19
	v_sub_f32_e32 v39, v39, v38
	v_mul_f32_e32 v39, 0x3fb8aa3b, v39
	v_sub_f32_e32 v26, v56, v38
	v_exp_f32_e32 v56, v39
	v_sub_f32_e32 v39, v55, v38
	v_mul_f32_e32 v39, 0x3fb8aa3b, v39
	v_exp_f32_e32 v55, v39
	v_sub_f32_e32 v39, v54, v38
	v_mul_f32_e32 v39, 0x3fb8aa3b, v39
	v_sub_f32_e32 v22, v59, v38
	v_exp_f32_e32 v59, v39
	v_sub_f32_e32 v39, v60, v38
	v_mul_f32_e32 v39, 0x3fb8aa3b, v39
	v_exp_f32_e32 v116, v39
	v_sub_f32_e32 v39, v58, v38
	v_mul_f32_e32 v39, 0x3fb8aa3b, v39
	v_exp_f32_e32 v117, v39
	v_sub_f32_e32 v39, v64, v38
	v_mul_f32_e32 v39, 0x3fb8aa3b, v39
	v_exp_f32_e32 v118, v39
	v_sub_f32_e32 v39, v61, v38
	v_mul_f32_e32 v39, 0x3fb8aa3b, v39
	v_exp_f32_e32 v119, v39
	v_sub_f32_e32 v39, v67, v38
	v_sub_f32_e32 v18, v63, v38
	v_mul_f32_e32 v39, 0x3fb8aa3b, v39
	v_mul_f32_e32 v18, 0x3fb8aa3b, v18
	v_exp_f32_e32 v67, v39
	v_sub_f32_e32 v39, v66, v38
	v_exp_f32_e32 v18, v18
	v_mul_f32_e32 v22, 0x3fb8aa3b, v22
	v_sub_f32_e32 v23, v62, v38
	v_mul_f32_e32 v39, 0x3fb8aa3b, v39
	v_exp_f32_e32 v22, v22
	v_mul_f32_e32 v23, 0x3fb8aa3b, v23
	v_exp_f32_e32 v66, v39
	v_sub_f32_e32 v39, v105, v38
	v_exp_f32_e32 v23, v23
	v_mul_f32_e32 v26, 0x3fb8aa3b, v26
	v_sub_f32_e32 v27, v65, v38
; #define LAS __attribute__((address_space(3)))
; DI unsigned pk2(float lo, float hi) { f32x2 v = {lo, hi}; bf16v2 b = __builtin_convertvector(v, bf16v2); return __builtin_bit_cast(unsigned, b); }
; #define MFMA32(a, b, c) __builtin_amdgcn_mfma_f32_16x16x32_bf16((a), (b), (c), 0, 0, 0)
; DI void na_phase(LAS unsigned char* lds, const Args& A, const bf16* proj, bf16* nao, int T, int nB, unsigned* counter, int tid_in) {
;     ...
;             float lsum = 0.f;
; #pragma unroll
;             for (int rr = 0; rr < 4; ++rr)
; #pragma unroll
;                 for (int ct = 0; ct < 2; ++ct)
; #pragma unroll
;                     for (int e = 0; e < 4; ++e) { const float p = __expf(sT[rr][ct][e] - mx); sT[rr][ct][e] = p; lsum += p; }
;             lsum += __shfl_xor(lsum, 16); lsum += __shfl_xor(lsum, 32);
;             f32x4 O[4];
; #pragma unroll
;             for (int mt = 0; mt < 4; ++mt) O[mt] = (f32x4){0.f, 0.f, 0.f, 0.f};
; #pragma unroll
;             for (int rr = 0; rr < 4; ++rr) { const int sl = (rs + 4 * kh + rr) & 7;
;                 const u32x4 pw = (u32x4){pk2(sT[rr][0][0], sT[rr][0][1]), pk2(sT[rr][0][2], sT[rr][0][3]), pk2(sT[rr][1][0], sT[rr][1][1]), pk2(sT[rr][1][2], sT[rr][1][3])};
;                 const bf16x8 pb = __builtin_bit_cast(bf16x8, pw);
; #pragma unroll
;                 for (int mt = 0; mt < 4; ++mt) { const int dd = 16 * mt + l15, sw = 2 * ((dd >> 1) & 7);
;                     const LAS unsigned char* vb = lds + NA_V + sl * 8192 + dd * 128;
;                     const u32x2 lo = *(const LAS u32x2*)(vb + ((((cs0 >> 2) + g) ^ sw) * 8)), hi = *(const LAS u32x2*)(vb + ((((cs0 >> 2) + 4 + g) ^ sw) * 8));
;                     const u32x4 vv = (u32x4){lo.x, lo.y, hi.x, hi.y};
;                     O[mt] = MFMA32(__builtin_bit_cast(bf16x8, vv), pb, O[mt]); } }
	v_mul_f32_e32 v39, 0x3fb8aa3b, v39
	v_exp_f32_e32 v26, v26
	v_mul_f32_e32 v27, 0x3fb8aa3b, v27
	v_exp_f32_e32 v120, v39
	v_sub_f32_e32 v39, v104, v38
	v_add_f32_e32 v19, 0, v18
	v_exp_f32_e32 v27, v27
	v_mul_f32_e32 v39, 0x3fb8aa3b, v39
	v_add_f32_e32 v19, v22, v19
	v_exp_f32_e32 v121, v39
	v_sub_f32_e32 v39, v107, v38
	v_add_f32_e32 v19, v23, v19
	v_mul_f32_e32 v39, 0x3fb8aa3b, v39
	v_add_f32_e32 v19, v26, v19
	v_exp_f32_e32 v122, v39
	v_sub_f32_e32 v39, v106, v38
	v_add_f32_e32 v19, v27, v19
	v_mul_f32_e32 v39, 0x3fb8aa3b, v39
	v_add_f32_e32 v19, v56, v19
	v_exp_f32_e32 v123, v39
	v_sub_f32_e32 v39, v109, v38
	v_add_f32_e32 v19, v55, v19
	v_mul_f32_e32 v39, 0x3fb8aa3b, v39
	v_add_f32_e32 v19, v59, v19
	v_exp_f32_e32 v124, v39
	v_sub_f32_e32 v39, v108, v38
	v_add_f32_e32 v19, v116, v19
	v_mul_f32_e32 v39, 0x3fb8aa3b, v39
	v_add_f32_e32 v19, v117, v19
	v_exp_f32_e32 v125, v39
	v_sub_f32_e32 v39, v111, v38
	v_add_f32_e32 v19, v118, v19
	v_mul_f32_e32 v39, 0x3fb8aa3b, v39
	v_add_f32_e32 v19, v119, v19
	v_exp_f32_e32 v126, v39
	v_sub_f32_e32 v39, v110, v38
	v_add_f32_e32 v19, v67, v19
	v_mul_f32_e32 v39, 0x3fb8aa3b, v39
	v_add_f32_e32 v19, v66, v19
	v_exp_f32_e32 v127, v39
	v_sub_f32_e32 v39, v113, v38
	v_add_f32_e32 v19, v120, v19
	v_mul_f32_e32 v39, 0x3fb8aa3b, v39
	v_add_f32_e32 v19, v121, v19
	v_exp_f32_e32 v128, v39
	v_sub_f32_e32 v39, v112, v38
	v_add_f32_e32 v19, v122, v19
	v_mul_f32_e32 v39, 0x3fb8aa3b, v39
	v_add_f32_e32 v19, v123, v19
	v_exp_f32_e32 v129, v39
	v_sub_f32_e32 v39, v115, v38
	v_add_f32_e32 v19, v124, v19
	v_mul_f32_e32 v39, 0x3fb8aa3b, v39
	v_add_f32_e32 v19, v125, v19
	v_exp_f32_e32 v130, v39
	v_sub_f32_e32 v39, v114, v38
	v_add_f32_e32 v19, v126, v19
	v_mul_f32_e32 v39, 0x3fb8aa3b, v39
	v_sub_f32_e32 v25, v25, v38
	v_add_f32_e32 v19, v127, v19
	v_exp_f32_e32 v131, v39
	v_mul_f32_e32 v25, 0x3fb8aa3b, v25
	v_sub_f32_e32 v24, v24, v38
	v_add_f32_e32 v19, v128, v19
	v_exp_f32_e32 v132, v25
	v_mul_f32_e32 v24, 0x3fb8aa3b, v24
	v_sub_f32_e32 v21, v21, v38
	v_add_f32_e32 v19, v129, v19
	v_exp_f32_e32 v133, v24
	v_mul_f32_e32 v21, 0x3fb8aa3b, v21
	v_sub_f32_e32 v20, v20, v38
	v_add_f32_e32 v19, v130, v19
	v_exp_f32_e32 v134, v21
	v_mul_f32_e32 v20, 0x3fb8aa3b, v20
	v_sub_f32_e32 v17, v17, v38
	v_add_f32_e32 v19, v131, v19
	v_exp_f32_e32 v135, v20
	v_mul_f32_e32 v17, 0x3fb8aa3b, v17
	v_sub_f32_e32 v16, v16, v38
	v_add_f32_e32 v19, v132, v19
	v_exp_f32_e32 v136, v17
	v_mul_f32_e32 v16, 0x3fb8aa3b, v16
	v_add_f32_e32 v19, v133, v19
	v_exp_f32_e32 v137, v16
	v_add_f32_e32 v19, v134, v19
	v_add_f32_e32 v19, v135, v19
	v_add_f32_e32 v17, v136, v19
	v_add_f32_e32 v16, v137, v17
	v_mov_b32_e32 v17, v16
	s_nop 1
	v_permlane16_swap_b32_e32 v17, v16
	v_add_u32_e32 v24, v74, v28
	v_cvt_pk_bf16_f32 v19, v55, v59
	v_add_u32_e32 v28, v24, v75
	v_add_u32_e32 v55, v24, v76
	s_waitcnt lgkmcnt(0)
	v_add_f32_e32 v39, v16, v17
	v_cvt_pk_bf16_f32 v16, v18, v22
	v_cvt_pk_bf16_f32 v17, v23, v26
	v_cvt_pk_bf16_f32 v18, v27, v56
	ds_read2st64_b64 v[20:23], v28 offset1:4
	ds_read2st64_b64 v[24:27], v55 offset1:4
	v_mov_b32_e32 v54, v39
	s_nop 1
	v_permlane32_swap_b32_e32 v54, v39
	s_waitcnt lgkmcnt(1)
	v_mov_b32_e32 v58, v20
	s_waitcnt lgkmcnt(0)
	v_mov_b32_e32 v60, v24
	v_mov_b32_e32 v61, v25
	v_mov_b32_e32 v24, v22
	v_mov_b32_e32 v25, v23
	v_mov_b32_e32 v59, v21
	v_add_f32_e32 v54, v39, v54
	v_mfma_f32_16x16x32_bf16 v[20:23], v[24:27], v[16:19], 0
	ds_read2st64_b64 v[24:27], v28 offset0:8 offset1:12
	ds_read2st64_b64 v[62:65], v55 offset0:8 offset1:12
	v_add_u32_e32 v28, v74, v29
	v_add_u32_e32 v29, v28, v75
	v_add_u32_e32 v28, v28, v76
	s_waitcnt lgkmcnt(1)
	v_mov_b32_e32 v104, v24
	v_mov_b32_e32 v105, v25
	s_waitcnt lgkmcnt(0)
; #define LAS __attribute__((address_space(3)))
; DI unsigned pk2(float lo, float hi) { f32x2 v = {lo, hi}; bf16v2 b = __builtin_convertvector(v, bf16v2); return __builtin_bit_cast(unsigned, b); }
; #define MFMA32(a, b, c) __builtin_amdgcn_mfma_f32_16x16x32_bf16((a), (b), (c), 0, 0, 0)
; DI void na_phase(LAS unsigned char* lds, const Args& A, const bf16* proj, bf16* nao, int T, int nB, unsigned* counter, int tid_in) {
;     ...
; #pragma unroll
;             for (int rr = 0; rr < 4; ++rr) { const int sl = (rs + 4 * kh + rr) & 7;
;                 const u32x4 pw = (u32x4){pk2(sT[rr][0][0], sT[rr][0][1]), pk2(sT[rr][0][2], sT[rr][0][3]), pk2(sT[rr][1][0], sT[rr][1][1]), pk2(sT[rr][1][2], sT[rr][1][3])};
;                 const bf16x8 pb = __builtin_bit_cast(bf16x8, pw);
; #pragma unroll
;                 for (int mt = 0; mt < 4; ++mt) { const int dd = 16 * mt + l15, sw = 2 * ((dd >> 1) & 7);
;                     const LAS unsigned char* vb = lds + NA_V + sl * 8192 + dd * 128;
;                     const u32x2 lo = *(const LAS u32x2*)(vb + ((((cs0 >> 2) + g) ^ sw) * 8)), hi = *(const LAS u32x2*)(vb + ((((cs0 >> 2) + 4 + g) ^ sw) * 8));
;                     const u32x4 vv = (u32x4){lo.x, lo.y, hi.x, hi.y};
;                     O[mt] = MFMA32(__builtin_bit_cast(bf16x8, vv), pb, O[mt]); } }
;             LAS float* MG = (LAS float*)(lds + NA_MRG + qg * 4608) + lane;
;             if (kh == 1) { MG[0] = mx; MG[64] = lsum;
; #pragma unroll
;                 for (int mt = 0; mt < 4; ++mt)
; #pragma unroll
;                     for (int e = 0; e < 4; ++e) MG[(2 + mt * 4 + e) * 64] = O[mt][e]; }
	v_mov_b32_e32 v106, v62
	v_mov_b32_e32 v107, v63
	v_mov_b32_e32 v62, v26
	v_mov_b32_e32 v63, v27
	v_mfma_f32_16x16x32_bf16 v[58:61], v[58:61], v[16:19], 0
	ds_read2st64_b64 v[108:111], v28 offset1:4
	v_cvt_pk_bf16_f32 v24, v116, v117
	v_cvt_pk_bf16_f32 v25, v118, v119
	v_mfma_f32_16x16x32_bf16 v[104:107], v[104:107], v[16:19], 0
	v_cvt_pk_bf16_f32 v26, v67, v66
	s_waitcnt lgkmcnt(0)
	v_mov_b32_e32 v114, v108
	v_mov_b32_e32 v115, v109
	v_mfma_f32_16x16x32_bf16 v[16:19], v[62:65], v[16:19], 0
	ds_read2st64_b64 v[62:65], v29 offset1:4
	v_cvt_pk_bf16_f32 v27, v120, v121
	s_waitcnt lgkmcnt(0)
	v_mov_b32_e32 v108, v64
	v_mov_b32_e32 v109, v65
	v_mov_b32_e32 v112, v62
	v_mov_b32_e32 v113, v63
	v_mfma_f32_16x16x32_bf16 v[20:23], v[108:111], v[24:27], v[20:23]
	ds_read2st64_b64 v[62:65], v29 offset0:8 offset1:12
	ds_read2st64_b64 v[108:111], v28 offset0:8 offset1:12
	v_add_u32_e32 v28, v74, v30
	v_add_u32_e32 v29, v28, v75
	v_mfma_f32_16x16x32_bf16 v[58:61], v[112:115], v[24:27], v[58:61]
	v_add_u32_e32 v28, v28, v76
	s_waitcnt lgkmcnt(0)
	v_mov_b32_e32 v114, v108
	v_mov_b32_e32 v115, v109
	v_mov_b32_e32 v108, v64
	v_mov_b32_e32 v109, v65
	v_mov_b32_e32 v112, v62
	v_mov_b32_e32 v113, v63
	v_mfma_f32_16x16x32_bf16 v[16:19], v[108:111], v[24:27], v[16:19]
	ds_read2st64_b64 v[62:65], v29 offset1:4
	ds_read2st64_b64 v[108:111], v28 offset1:4
	v_mfma_f32_16x16x32_bf16 v[104:107], v[112:115], v[24:27], v[104:107]
	v_cvt_pk_bf16_f32 v24, v122, v123
	v_cvt_pk_bf16_f32 v25, v124, v125
	s_waitcnt lgkmcnt(0)
	v_mov_b32_e32 v114, v108
	v_mov_b32_e32 v115, v109
	v_mov_b32_e32 v108, v64
	v_mov_b32_e32 v109, v65
	v_cvt_pk_bf16_f32 v26, v126, v127
	v_cvt_pk_bf16_f32 v27, v128, v129
	v_mov_b32_e32 v112, v62
	v_mov_b32_e32 v113, v63
	v_mfma_f32_16x16x32_bf16 v[20:23], v[108:111], v[24:27], v[20:23]
	ds_read2st64_b64 v[62:65], v29 offset0:8 offset1:12
	ds_read2st64_b64 v[108:111], v28 offset0:8 offset1:12
	v_add_u32_e32 v28, v74, v31
	v_add_u32_e32 v55, v28, v75
	v_mfma_f32_16x16x32_bf16 v[58:61], v[112:115], v[24:27], v[58:61]
	s_waitcnt lgkmcnt(1)
	v_mov_b32_e32 v112, v62
	v_mov_b32_e32 v113, v63
	s_waitcnt lgkmcnt(0)
	v_mov_b32_e32 v114, v108
	v_mov_b32_e32 v115, v109
	v_mov_b32_e32 v108, v64
	v_mov_b32_e32 v109, v65
	v_add_u32_e32 v56, v28, v76
	v_mfma_f32_16x16x32_bf16 v[104:107], v[112:115], v[24:27], v[104:107]
	v_cvt_pk_bf16_f32 v62, v130, v131
	v_cvt_pk_bf16_f32 v63, v132, v133
	v_cvt_pk_bf16_f32 v64, v134, v135
	v_mfma_f32_16x16x32_bf16 v[16:19], v[108:111], v[24:27], v[16:19]
	ds_read2st64_b64 v[24:27], v55 offset1:4
	ds_read2st64_b64 v[108:111], v56 offset1:4
	v_cvt_pk_bf16_f32 v65, v136, v137
	s_waitcnt lgkmcnt(1)
	v_mov_b32_e32 v28, v24
	v_mov_b32_e32 v29, v25
	s_waitcnt lgkmcnt(0)
	v_mov_b32_e32 v30, v108
	v_mov_b32_e32 v31, v109
	v_mov_b32_e32 v108, v26
	v_mov_b32_e32 v109, v27
	v_mfma_f32_16x16x32_bf16 v[28:31], v[28:31], v[62:65], v[58:61]
	s_nop 0
	v_mfma_f32_16x16x32_bf16 v[24:27], v[108:111], v[62:65], v[20:23]
	s_nop 0
	ds_read2st64_b64 v[58:61], v55 offset0:8 offset1:12
	ds_read2st64_b64 v[108:111], v56 offset0:8 offset1:12
	s_waitcnt lgkmcnt(1)
	v_mov_b32_e32 v20, v58
	v_mov_b32_e32 v21, v59
	s_waitcnt lgkmcnt(0)
	v_mov_b32_e32 v22, v108
	v_mov_b32_e32 v23, v109
	v_mov_b32_e32 v108, v60
	v_mov_b32_e32 v109, v61
	v_mfma_f32_16x16x32_bf16 v[20:23], v[20:23], v[62:65], v[104:107]
	s_nop 0
	v_mfma_f32_16x16x32_bf16 v[16:19], v[108:111], v[62:65], v[16:19]
	s_and_saveexec_b64 s[0:1], s[42:43]
	s_cbranch_execz .LBB0_403
	ds_write2st64_b32 v103, v38, v54 offset1:1
	ds_write2st64_b32 v103, v28, v29 offset0:2 offset1:3
	ds_write2st64_b32 v103, v30, v31 offset0:4 offset1:5
	ds_write2st64_b32 v103, v24, v25 offset0:6 offset1:7
	ds_write2st64_b32 v103, v26, v27 offset0:8 offset1:9
	ds_write2st64_b32 v103, v20, v21 offset0:10 offset1:11
	ds_write2st64_b32 v103, v22, v23 offset0:12 offset1:13
	ds_write2st64_b32 v103, v16, v17 offset0:14 offset1:15
	ds_write2st64_b32 v103, v18, v19 offset0:16 offset1:17
